# P3 cmp_task: V^T tile staged into the wave's LDS by LDS-DMA at task start, PV fragment reads become ds_read (ticket counters moved to LDS 0x20100); on top of dynamic rows/cmp
# speedup vs baseline: 1.0053x; 1.0015x over previous
; __global__ void __launch_bounds__(NTHR, 2) fwd_kernel(Args a) {
;     ...
;     {
;         const int nrow = (MTOK - gw + NGW - 1) / NGW, ncmp = (8192 - gw + NGW - 1) / NGW;
;         const int stride = nrow > 0 && ncmp > 0 ? (nrow / ncmp > 0 ? nrow / ncmp : 1) : 1, phase = ((wave >> 2) * (stride >> 1) + (wave & 1)) % stride;
;         int ci = 0;
;         for (int i = 0; i < nrow || ci < ncmp; ++i) {
.LBB0_472:
	s_or_b64 exec, exec, s[4:5]
	s_sub_i32 s4, s20, s92
	s_add_i32 s5, s4, 0x7fff
	s_sub_i32 s7, 0xffff8001, s4
	s_ashr_i32 s6, s5, 31
	s_max_i32 s5, s5, s7
	s_mul_hi_u32 s7, s5, s73
	s_mul_i32 s8, s7, s21
	s_sub_i32 s5, s5, s8
	s_xor_b32 s6, s6, s72
	s_add_i32 s8, s7, 1
	s_sub_i32 s9, s5, s21
	s_cmp_ge_u32 s5, s21
	s_cselect_b32 s7, s8, s7
	s_cselect_b32 s5, s9, s5
	s_add_i32 s8, s7, 1
	s_cmp_ge_u32 s5, s21
	s_cselect_b32 s5, s8, s7
	s_xor_b32 s5, s5, s6
	s_sub_i32 s47, s5, s6
	s_add_i32 s5, s4, 0x1fff
	s_sub_i32 s4, 0xffffe001, s4
	s_max_i32 s4, s5, s4
	s_ashr_i32 s6, s5, 31
	s_mul_hi_u32 s5, s4, s73
	s_mul_i32 s7, s5, s21
	s_sub_i32 s4, s4, s7
	s_xor_b32 s6, s6, s72
	s_add_i32 s7, s5, 1
	s_sub_i32 s8, s4, s21
	s_cmp_ge_u32 s4, s21
	s_cselect_b32 s5, s7, s5
	s_cselect_b32 s4, s8, s4
	s_add_i32 s7, s5, 1
	s_cmp_ge_u32 s4, s21
	s_cselect_b32 s4, s7, s5
	s_xor_b32 s4, s4, s6
	s_sub_i32 s58, s4, s6
	s_cmp_gt_i32 s47, 0
	s_cselect_b64 s[8:9], -1, 0
	s_cmp_gt_i32 s58, 0
	s_cselect_b64 s[10:11], -1, 0
	s_and_b64 s[4:5], s[8:9], s[10:11]
	s_mov_b32 s69, 1
	s_and_b64 vcc, exec, s[4:5]
	v_mov_b32_e32 v1, 0x20100
	v_mov_b32_e32 v2, 0
	ds_write_b32 v1, v2
	ds_write_b32 v1, v2 offset:4
	s_waitcnt lgkmcnt(0)
	s_barrier
	s_cbranch_vccz .LBB0_474
	v_cvt_f32_u32_e32 v1, s58
	s_sub_i32 s4, 0, s58
	v_rcp_iflag_f32_e32 v1, v1
	s_nop 0
	v_mul_f32_e32 v1, 0x4f7ffffe, v1
	v_cvt_u32_f32_e32 v1, v1
	s_nop 0
	v_readfirstlane_b32 s5, v1
	s_mul_i32 s4, s4, s5
	s_mul_hi_u32 s4, s5, s4
	s_add_i32 s5, s5, s4
	s_mul_hi_u32 s4, s47, s5
	s_mul_i32 s5, s4, s58
	s_sub_i32 s5, s47, s5
	s_add_i32 s6, s4, 1
	s_sub_i32 s7, s5, s58
	s_cmp_ge_u32 s5, s58
	s_cselect_b32 s4, s6, s4
	s_cselect_b32 s5, s7, s5
	s_add_i32 s6, s4, 1
	s_cmp_ge_u32 s5, s58
	s_cselect_b32 s4, s6, s4
	s_cmp_le_u32 s58, s47
	s_cselect_b32 s69, s4, 1
.LBB0_474:
	s_mov_b32 s69, 3
	v_cvt_f32_u32_e32 v1, s69
	s_add_u32 s21, s18, 0x6000000
	s_addc_u32 s68, s19, 0
	s_add_u32 s12, s18, 0x6800000
	v_rcp_iflag_f32_e32 v1, v1
	s_addc_u32 s13, s19, 0
	s_or_b64 s[4:5], s[8:9], s[10:11]
	s_andn2_b64 vcc, exec, s[4:5]
	v_mul_f32_e32 v1, 0x4f7ffffe, v1
	v_cvt_u32_f32_e32 v1, v1
	s_nop 0
	v_readfirstlane_b32 s59, v1
	s_cbranch_vccnz .LBB0_659
	v_lshlrev_b32_e32 v1, 6, v133
	v_or_b32_e32 v37, 47, v1
	v_or_b32_e32 v46, 31, v1
	v_or_b32_e32 v117, 63, v1
	v_add_u32_e32 v119, 0x4f, v1
	v_or_b32_e32 v39, 0xaf, v1
	v_or_b32_e32 v48, 0x9f, v1
	v_or_b32_e32 v202, 0xbf, v1
	v_add_u32_e32 v203, 0xcf, v1
	v_or_b32_e32 v47, 0x12f, v1
	v_or_b32_e32 v50, 0x11f, v1
	v_or_b32_e32 v204, 0x13f, v1
	v_add_u32_e32 v205, 0x14f, v1
	v_or_b32_e32 v49, 0x1af, v1
	v_or_b32_e32 v52, 0x19f, v1
	v_or_b32_e32 v206, 0x1bf, v1
	v_add_u32_e32 v207, 0x1cf, v1
	v_or_b32_e32 v51, 0x22f, v1
	v_or_b32_e32 v54, 0x21f, v1
	v_or_b32_e32 v208, 0x23f, v1
	v_add_u32_e32 v209, 0x24f, v1
	v_or_b32_e32 v53, 0x2af, v1
	v_or_b32_e32 v56, 0x29f, v1
	v_or_b32_e32 v210, 0x2bf, v1
	v_add_u32_e32 v211, 0x2cf, v1
	v_or_b32_e32 v55, 0x32f, v1
	v_or_b32_e32 v58, 0x31f, v1
	v_or_b32_e32 v212, 0x33f, v1
	v_add_u32_e32 v213, 0x34f, v1
	v_or_b32_e32 v57, 0x3af, v1
	v_or_b32_e32 v60, 0x39f, v1
	v_or_b32_e32 v216, 0x3bf, v1
	v_add_u32_e32 v217, 0x3cf, v1
	v_or_b32_e32 v59, 0x42f, v1
	v_or_b32_e32 v62, 0x41f, v1
	v_or_b32_e32 v218, 0x43f, v1
	v_add_u32_e32 v219, 0x44f, v1
	v_or_b32_e32 v61, 0x4af, v1
	v_or_b32_e32 v64, 0x49f, v1
	v_or_b32_e32 v220, 0x4bf, v1
	v_add_u32_e32 v221, 0x4cf, v1
	v_or_b32_e32 v63, 0x52f, v1
	v_or_b32_e32 v66, 0x51f, v1
	v_or_b32_e32 v222, 0x53f, v1
	v_add_u32_e32 v223, 0x54f, v1
	v_or_b32_e32 v65, 0x5af, v1
	v_or_b32_e32 v68, 0x59f, v1
	v_or_b32_e32 v224, 0x5bf, v1
	v_add_u32_e32 v225, 0x5cf, v1
	v_or_b32_e32 v67, 0x62f, v1
	v_or_b32_e32 v70, 0x61f, v1
	v_or_b32_e32 v226, 0x63f, v1
	v_add_u32_e32 v227, 0x64f, v1
	v_or_b32_e32 v69, 0x6af, v1
	v_or_b32_e32 v72, 0x69f, v1
	v_or_b32_e32 v228, 0x6bf, v1
	v_add_u32_e32 v229, 0x6cf, v1
	v_or_b32_e32 v71, 0x72f, v1
	v_or_b32_e32 v74, 0x71f, v1
	v_or_b32_e32 v230, 0x73f, v1
	v_add_u32_e32 v231, 0x74f, v1
	v_or_b32_e32 v73, 0x7af, v1
	v_or_b32_e32 v76, 0x79f, v1
	v_or_b32_e32 v232, 0x7bf, v1
	v_add_u32_e32 v233, 0x7cf, v1
	v_lshl_or_b32 v1, v214, 3, v133
	v_cmp_lt_u32_e64 s[16:17], 2, v1
	v_cmp_lt_u32_e64 s[26:27], 10, v1
	v_cmp_lt_u32_e64 s[38:39], 18, v1
	v_writelane_b32 v253, s16, 6
	v_mov_b32_e32 v43, 0
	v_lshlrev_b32_e32 v40, 1, v139
	v_writelane_b32 v253, s17, 7
	v_cmp_lt_u32_e64 s[16:17], 4, v1
	v_mov_b32_e32 v41, v43
	v_or_b32_e32 v2, 2, v1
	v_writelane_b32 v253, s16, 8
	v_lshl_add_u64 v[44:45], s[48:49], 0, v[40:41]
	v_cmp_lt_u32_e64 s[48:49], 4, v2
	v_writelane_b32 v253, s17, 9
	v_cmp_lt_u32_e64 s[16:17], 6, v1
	s_lshr_b32 s4, s78, 8
	s_lshr_b32 s5, s69, 1
	v_writelane_b32 v253, s16, 10
	s_mul_i32 s4, s5, s4
	s_bfe_u32 s5, s78, 0x10006
	v_writelane_b32 v253, s17, 11
	v_cmp_lt_u32_e64 s[16:17], 8, v1
	s_add_i32 s4, s4, s5
	s_sub_i32 s5, 0, s69
	v_writelane_b32 v253, s16, 12
	s_mul_i32 s5, s5, s59
	s_mul_hi_u32 s5, s59, s5
	v_writelane_b32 v253, s17, 13
	v_writelane_b32 v253, s26, 14
	s_add_i32 s59, s59, s5
	s_mul_hi_u32 s5, s4, s59
	v_writelane_b32 v253, s27, 15
	v_cmp_lt_u32_e64 s[26:27], 12, v1
	s_mul_i32 s5, s5, s69
	s_sub_i32 s4, s4, s5
	v_writelane_b32 v253, s26, 16
	s_sub_i32 s5, s4, s69
	s_cmp_ge_u32 s4, s69
	v_writelane_b32 v253, s27, 17
	v_cmp_lt_u32_e64 s[26:27], 14, v1
	s_cselect_b32 s4, s5, s4
	s_sub_i32 s5, s4, s69
	v_writelane_b32 v253, s26, 18
	v_cmp_ne_u32_e64 s[6:7], 0, v1
	v_lshlrev_b32_e64 v237, v1, 1
	v_writelane_b32 v253, s27, 19
	v_cmp_lt_u32_e64 s[26:27], 16, v1
	v_lshlrev_b32_e64 v238, v1, 4
	v_lshlrev_b32_e64 v239, v1, 16
	v_writelane_b32 v253, s26, 20
	v_lshlrev_b32_e64 v240, v1, 64
; DI void cmp_task(const bf16_t* Z, const bf16_t* KCC, const bf16_t* VCT, bf16_t* OCMP, unsigned* selm, int b, int hk, int tg, int lane) {
;     ...
;         unsigned word = 0u;
; #pragma unroll
;         for (int mm = 0; mm < 4; ++mm) {
;             const int jm = 8 * g + 2 * mm + h; const float v = mine[mm]; int rank = 0;
; #pragma unroll
;             for (int T = 0; T < 4; ++T)
; #pragma unroll
;                 for (int m2 = 0; m2 < 4; ++m2) { const int je = 8 * T + 2 * m2;
;                     rank += (ev[T][m2] > v || (ev[T][m2] == v && je < jm)) ? 1 : 0; rank += (od[T][m2] > v || (od[T][m2] == v && je + 1 < jm)) ? 1 : 0; }
;             if (v >= 0.f && rank < 5) word |= 1u << jm;
	s_cmp_ge_u32 s4, s69
	v_writelane_b32 v253, s27, 21
	v_writelane_b32 v253, s38, 22
	v_mov_b32_e32 v139, v43
	v_lshlrev_b32_e32 v88, 2, v135
	v_writelane_b32 v253, s39, 23
	v_cmp_lt_u32_e64 s[38:39], 20, v1
	v_lshlrev_b32_e32 v241, 2, v242
	v_cmp_eq_u32_e64 s[74:75], 0, v242
	v_writelane_b32 v253, s38, 24
	v_lshlrev_b32_e32 v242, 5, v135
	s_cselect_b32 s60, s5, s4
	v_writelane_b32 v253, s39, 25
	v_cmp_lt_u32_e64 s[38:39], 22, v1
	v_lshrrev_b32_e32 v113, 2, v134
	v_lshlrev_b32_e32 v115, 6, v214
	v_writelane_b32 v253, s38, 26
	v_lshlrev_b32_e32 v38, 6, v134
	v_lshl_add_u64 v[78:79], s[14:15], 0, v[138:139]
	v_writelane_b32 v253, s39, 27
	v_writelane_b32 v253, s48, 28
	v_cmp_eq_u32_e64 s[38:39], 25, v1
	v_or_b32_e32 v80, 0x1000, v136
	v_writelane_b32 v253, s49, 29
	v_cmp_lt_u32_e64 s[48:49], 5, v2
	v_cmp_gt_u32_e64 s[4:5], 32, v135
	v_or_b32_e32 v84, 20, v133
	v_writelane_b32 v253, s48, 30
	v_or_b32_e32 v36, 18, v133
	v_or_b32_e32 v236, 24, v133
	v_writelane_b32 v253, s49, 31
	v_cmp_lt_u32_e64 s[48:49], 6, v2
	v_or_b32_e32 v81, 28, v133
	s_mov_b32 s15, 0
	v_writelane_b32 v253, s48, 32
	v_cmp_lt_u32_e64 s[16:17], 1, v214
	v_cmp_ne_u32_e64 s[26:27], 0, v214
	v_writelane_b32 v253, s49, 33
	v_cmp_lt_u32_e64 s[48:49], 8, v2
	v_cmp_eq_u32_e64 s[28:29], 3, v214
	v_or_b32_e32 v83, 0x101, v88
	v_writelane_b32 v253, s48, 34
	v_or_b32_e32 v90, 0x100, v88
	v_or_b32_e32 v85, 0x103, v88
	v_writelane_b32 v253, s49, 35
	v_cmp_lt_u32_e64 s[48:49], 9, v2
	v_or_b32_e32 v92, 0x102, v88
	v_or_b32_e32 v87, 0x201, v88
	v_writelane_b32 v253, s48, 36
	v_or_b32_e32 v86, 0x200, v88
	v_or_b32_e32 v89, 0x203, v88
	v_writelane_b32 v253, s49, 37
	v_cmp_lt_u32_e64 s[48:49], 10, v2
	v_or_b32_e32 v91, 0x301, v88
	v_or_b32_e32 v98, 0x300, v88
	v_writelane_b32 v253, s48, 38
	v_or_b32_e32 v93, 0x303, v88
	v_or_b32_e32 v100, 0x302, v88
	v_writelane_b32 v253, s49, 39
	v_cmp_lt_u32_e64 s[48:49], 16, v2
	v_or_b32_e32 v102, 0x400, v88
	v_or_b32_e32 v104, 0x402, v88
	v_writelane_b32 v253, s48, 40
	v_or_b32_e32 v99, 0x501, v88
	v_or_b32_e32 v106, 0x500, v88
	v_writelane_b32 v253, s49, 41
	v_cmp_lt_u32_e64 s[48:49], 12, v2
	v_or_b32_e32 v101, 0x503, v88
	v_or_b32_e32 v108, 0x502, v88
	v_writelane_b32 v253, s48, 42
	v_or_b32_e32 v103, 0x601, v88
	v_or_b32_e32 v110, 0x600, v88
	v_writelane_b32 v253, s49, 43
	v_cmp_lt_u32_e64 s[48:49], 17, v2
	v_or_b32_e32 v105, 0x603, v88
	v_or_b32_e32 v112, 0x602, v88
	v_writelane_b32 v253, s48, 44
	v_or_b32_e32 v107, 0x701, v88
	v_or_b32_e32 v114, 0x700, v88
	v_writelane_b32 v253, s49, 45
	v_cmp_lt_u32_e64 s[48:49], 13, v2
	v_or_b32_e32 v109, 0x703, v88
	v_or_b32_e32 v116, 0x702, v88
	v_writelane_b32 v253, s48, 46
	v_or_b32_e32 v243, 31, v242
	s_mov_b32 s46, 0x3e38aa3b
	v_writelane_b32 v253, s49, 47
	v_cmp_lt_u32_e64 s[48:49], 18, v2
	s_mov_b32 s61, 0xff800000
	s_mov_b32 s62, -1.0
	v_writelane_b32 v253, s48, 48
	v_lshlrev_b32_e32 v120, 2, v88
	v_mov_b32_e32 v244, 0x2200
	v_writelane_b32 v253, s49, 49
	v_cmp_lt_u32_e64 s[48:49], 14, v2
	v_mov_b32_e32 v245, 0xff800000
	s_mov_b32 s63, 0
	v_writelane_b32 v253, s48, 50
	s_mov_b32 s64, 0
	s_nop 0
	v_writelane_b32 v253, s49, 51
	v_cmp_lt_u32_e64 s[48:49], 20, v2
	s_nop 1
	v_writelane_b32 v253, s48, 52
	s_nop 1
	v_writelane_b32 v253, s49, 53
	v_cmp_lt_u32_e64 s[48:49], 21, v2
	s_nop 1
	v_writelane_b32 v253, s48, 54
	s_nop 1
	v_writelane_b32 v253, s49, 55
	v_cmp_lt_u32_e64 s[48:49], 22, v2
	s_nop 1
	v_writelane_b32 v253, s48, 56
	s_nop 1
	v_writelane_b32 v253, s49, 57
	v_cmp_lt_u32_e64 s[48:49], 24, v2
	s_nop 1
	v_writelane_b32 v253, s48, 58
	s_nop 1
	v_writelane_b32 v253, s49, 59
	v_cmp_lt_u32_e64 s[48:49], 25, v2
	v_or_b32_e32 v2, 4, v1
	s_nop 0
	v_writelane_b32 v253, s48, 60
	s_nop 1
	v_writelane_b32 v253, s49, 61
	v_cmp_lt_u32_e64 s[48:49], 5, v2
	s_nop 1
	v_writelane_b32 v253, s48, 62
	s_nop 1
	v_writelane_b32 v253, s49, 63
	v_cmp_lt_u32_e64 s[48:49], 6, v2
	s_nop 1
	v_writelane_b32 v254, s48, 0
	s_nop 1
	v_writelane_b32 v254, s49, 1
	v_cmp_lt_u32_e64 s[48:49], 8, v2
	s_nop 1
	v_writelane_b32 v254, s48, 2
	s_nop 1
	v_writelane_b32 v254, s49, 3
	v_cmp_lt_u32_e64 s[48:49], 9, v2
	s_nop 1
	v_writelane_b32 v254, s48, 4
	s_nop 1
	v_writelane_b32 v254, s49, 5
	v_cmp_lt_u32_e64 s[48:49], 10, v2
	s_nop 1
	v_writelane_b32 v254, s48, 6
	s_nop 1
	v_writelane_b32 v254, s49, 7
	v_cmp_lt_u32_e64 s[48:49], 11, v2
	s_nop 1
	v_writelane_b32 v254, s48, 8
	s_nop 1
	v_writelane_b32 v254, s49, 9
	v_cmp_lt_u32_e64 s[48:49], 12, v2
	s_nop 1
	v_writelane_b32 v254, s48, 10
	s_nop 1
	v_writelane_b32 v254, s49, 11
	v_cmp_lt_u32_e64 s[48:49], 13, v2
	s_nop 1
; DI void cmp_task(const bf16_t* Z, const bf16_t* KCC, const bf16_t* VCT, bf16_t* OCMP, unsigned* selm, int b, int hk, int tg, int lane) {
;     ...
;         unsigned word = 0u;
; #pragma unroll
;         for (int mm = 0; mm < 4; ++mm) {
;             const int jm = 8 * g + 2 * mm + h; const float v = mine[mm]; int rank = 0;
; #pragma unroll
;             for (int T = 0; T < 4; ++T)
; #pragma unroll
;                 for (int m2 = 0; m2 < 4; ++m2) { const int je = 8 * T + 2 * m2;
;                     rank += (ev[T][m2] > v || (ev[T][m2] == v && je < jm)) ? 1 : 0; rank += (od[T][m2] > v || (od[T][m2] == v && je + 1 < jm)) ? 1 : 0; }
;             if (v >= 0.f && rank < 5) word |= 1u << jm;
; __global__ void __launch_bounds__(NTHR, 2) fwd_kernel(Args a) {
;     ...
;         for (int i = 0; i < nrow || ci < ncmp; ++i) {
;             if (ci < ncmp && (i >= nrow || (i % stride) == phase)) { const int task = gw + ci * NGW; ++ci;
	v_writelane_b32 v254, s48, 12
	s_nop 1
	v_writelane_b32 v254, s49, 13
	v_cmp_lt_u32_e64 s[48:49], 14, v2
	s_nop 1
	v_writelane_b32 v254, s48, 14
	s_nop 1
	v_writelane_b32 v254, s49, 15
	v_cmp_lt_u32_e64 s[48:49], 16, v2
	s_nop 1
	v_writelane_b32 v254, s48, 16
	s_nop 1
	v_writelane_b32 v254, s49, 17
	v_cmp_lt_u32_e64 s[48:49], 17, v2
	s_nop 1
	v_writelane_b32 v254, s48, 18
	s_nop 1
	v_writelane_b32 v254, s49, 19
	v_cmp_lt_u32_e64 s[48:49], 18, v2
	s_nop 1
	v_writelane_b32 v254, s48, 20
	s_nop 1
	v_writelane_b32 v254, s49, 21
	v_cmp_lt_u32_e64 s[48:49], 19, v2
	s_nop 1
	v_writelane_b32 v254, s48, 22
	s_nop 1
	v_writelane_b32 v254, s49, 23
	v_cmp_lt_u32_e64 s[48:49], 20, v2
	s_nop 1
	v_writelane_b32 v254, s48, 24
	s_nop 1
	v_writelane_b32 v254, s49, 25
	v_cmp_lt_u32_e64 s[48:49], 21, v2
	s_nop 1
	v_writelane_b32 v254, s48, 26
	s_nop 1
	v_writelane_b32 v254, s49, 27
	v_cmp_lt_u32_e64 s[48:49], 22, v2
	s_nop 1
	v_writelane_b32 v254, s48, 28
	s_nop 1
	v_writelane_b32 v254, s49, 29
	v_cmp_lt_u32_e64 s[48:49], 24, v2
	s_nop 1
	v_writelane_b32 v254, s48, 30
	s_nop 1
	v_writelane_b32 v254, s49, 31
	v_cmp_lt_u32_e64 s[48:49], 25, v2
	s_nop 1
	v_writelane_b32 v254, s48, 32
	s_nop 1
	v_writelane_b32 v254, s49, 33
	v_cmp_lt_u32_e64 s[48:49], 26, v2
	s_nop 1
	v_writelane_b32 v254, s48, 34
	s_nop 1
	v_writelane_b32 v254, s49, 35
	v_cmp_lt_u32_e64 s[48:49], 27, v2
	v_or_b32_e32 v2, 6, v1
	v_and_b32_e32 v1, 35, v0
	v_writelane_b32 v254, s48, 36
	v_cmp_lt_u32_e64 s[70:71], 29, v2
	v_cmp_eq_u32_e64 s[72:73], 0, v1
	v_writelane_b32 v254, s49, 37
	v_cmp_lt_u32_e64 s[48:49], 8, v2
	v_mbcnt_lo_u32_b32 v1, -1, 0
	v_mbcnt_hi_u32_b32 v246, -1, v1
	v_writelane_b32 v254, s48, 38
	s_nop 1
	v_writelane_b32 v254, s49, 39
	v_cmp_lt_u32_e64 s[48:49], 9, v2
	s_nop 1
	v_writelane_b32 v254, s48, 40
	s_nop 1
	v_writelane_b32 v254, s49, 41
	v_cmp_lt_u32_e64 s[48:49], 10, v2
	s_nop 1
	v_writelane_b32 v254, s48, 42
	s_nop 1
	v_writelane_b32 v254, s49, 43
	v_cmp_lt_u32_e64 s[48:49], 11, v2
	s_nop 1
	v_writelane_b32 v254, s48, 44
	s_nop 1
	v_writelane_b32 v254, s49, 45
	v_cmp_lt_u32_e64 s[48:49], 12, v2
	s_nop 1
	v_writelane_b32 v254, s48, 46
	s_nop 1
	v_writelane_b32 v254, s49, 47
	v_cmp_lt_u32_e64 s[48:49], 13, v2
	s_nop 1
	v_writelane_b32 v254, s48, 48
	s_nop 1
	v_writelane_b32 v254, s49, 49
	v_cmp_lt_u32_e64 s[48:49], 14, v2
	s_nop 1
	v_writelane_b32 v254, s48, 50
	s_nop 1
	v_writelane_b32 v254, s49, 51
	v_cmp_lt_u32_e64 s[48:49], 16, v2
	s_nop 1
	v_writelane_b32 v254, s48, 52
	s_nop 1
	v_writelane_b32 v254, s49, 53
	v_cmp_lt_u32_e64 s[48:49], 17, v2
	s_nop 1
	v_writelane_b32 v254, s48, 54
	s_nop 1
	v_writelane_b32 v254, s49, 55
	v_cmp_lt_u32_e64 s[48:49], 18, v2
	s_nop 1
	v_writelane_b32 v254, s48, 56
	s_nop 1
	v_writelane_b32 v254, s49, 57
	v_cmp_lt_u32_e64 s[48:49], 19, v2
	s_nop 1
	v_writelane_b32 v254, s48, 58
	s_nop 1
	v_writelane_b32 v254, s49, 59
	v_cmp_lt_u32_e64 s[48:49], 20, v2
	s_nop 1
	v_writelane_b32 v254, s48, 60
	s_nop 1
	v_writelane_b32 v254, s49, 61
	v_cmp_lt_u32_e64 s[48:49], 21, v2
	s_nop 1
	v_writelane_b32 v254, s48, 62
	s_nop 1
	v_writelane_b32 v254, s49, 63
	v_cmp_lt_u32_e64 s[48:49], 22, v2
	s_nop 1
	v_writelane_b32 v255, s48, 0
	s_nop 1
	v_writelane_b32 v255, s49, 1
	v_cmp_lt_u32_e64 s[48:49], 24, v2
	s_nop 1
	v_writelane_b32 v255, s48, 2
	s_nop 1
	v_writelane_b32 v255, s49, 3
	v_cmp_lt_u32_e64 s[48:49], 25, v2
	s_nop 1
	v_writelane_b32 v255, s48, 4
	s_nop 1
	v_writelane_b32 v255, s49, 5
	v_cmp_lt_u32_e64 s[48:49], 26, v2
	s_nop 1
	v_writelane_b32 v255, s48, 6
	s_nop 1
	v_writelane_b32 v255, s49, 7
	v_cmp_lt_u32_e64 s[48:49], 27, v2
	s_nop 1
	v_writelane_b32 v255, s48, 8
	s_nop 1
	v_writelane_b32 v255, s49, 9
	v_cmp_lt_u32_e64 s[48:49], 28, v2
	v_lshlrev_b64 v[2:3], v135, -1
	v_not_b32_e32 v111, v3
	v_writelane_b32 v255, s48, 10
	v_not_b32_e32 v118, v2
	s_nop 0
	v_writelane_b32 v255, s49, 11
	s_mov_b64 s[48:49], exec
	s_mov_b64 exec, 1
	v_mov_b32_e32 v1, 0x20100
	v_mov_b32_e32 v2, 1
	ds_add_rtn_u32 v2, v1, v2
	s_waitcnt lgkmcnt(0)
	v_readfirstlane_b32 s47, v2
	s_mov_b64 exec, s[48:49]
	s_cmpk_lt_u32 s47, 0x80
	s_cselect_b64 s[8:9], -1, 0
	s_branch .LBB0_477
.LBB0_476:
	s_add_i32 s64, s64, 1
	s_mov_b64 s[48:49], exec
	s_mov_b64 exec, 1
	v_mov_b32_e32 v1, 0x20100
	v_mov_b32_e32 v2, 1
	ds_add_rtn_u32 v2, v1, v2
	s_waitcnt lgkmcnt(0)
	v_readfirstlane_b32 s47, v2
	s_mov_b64 exec, s[48:49]
	s_cmpk_lt_u32 s47, 0x80
	s_cselect_b64 s[8:9], -1, 0
	s_cmp_lt_i32 s63, s58
	s_cselect_b64 s[10:11], -1, 0
	s_or_b64 s[48:49], s[8:9], s[10:11]
	s_andn2_b64 vcc, exec, s[48:49]
	s_cbranch_vccnz .LBB0_659

; #define MFMA32(a, b, c) __builtin_amdgcn_mfma_f32_32x32x16_bf16((a), (b), (c), 0, 0, 0)
; DI int crow(int r, int h) { return (r & 3) + 8 * (r >> 2) + 4 * h; }
; DI void cmp_task(const bf16_t* Z, const bf16_t* KCC, const bf16_t* VCT, bf16_t* OCMP, unsigned* selm, int b, int hk, int tg, int lane) {
;     const int r32 = lane & 31, h = lane >> 5;
;     const int tok = 8 * tg + (r32 >> 2), g = r32 & 3, head = hk * 4 + g;
;     const size_t grow = (size_t)b * SEQ + tok;
;     const bf16_t* zr = Z + grow * NZ;
;     bf16x8 qf[4];
; #pragma unroll
;     for (int s = 0; s < 4; ++s) qf[s] = *(const bf16x8*)(zr + ZC_QA + head * 64 + 16 * s + 8 * h);
;     const bf16_t* kc = KCC + (size_t)(b * 2 + hk) * 128 * 64; const bf16_t* vt = VCT + (size_t)(b * 2 + hk) * 64 * 128;
;     const int tmax = 8 * tg + 7;
;     const int nsub = tmax < 31 ? 0 : (((tmax - 31) >> 4) >> 5) + 1;
;     f32x16 p[4];
; #pragma unroll
;     for (int sub = 0; sub < 4; ++sub) {
;         if (sub < nsub) {
;             p[sub] = f16zero();
; #pragma unroll
;             for (int s = 0; s < 4; ++s) { const bf16x8 af = *(const bf16x8*)(kc + (size_t)(32 * sub + r32) * 64 + 16 * s + 8 * h); p[sub] = MFMA32(af, qf[s], p[sub]); }
; #pragma unroll
;             for (int r = 0; r < 16; ++r) { const int n = 32 * sub + crow(r, h); p[sub][r] = (16 * n + 31 <= tok) ? p[sub][r] * SM_C : NINF; }
; __global__ void __launch_bounds__(NTHR, 2) fwd_kernel(Args a) {
;     ...
;             if (ci < ncmp && (i >= nrow || (i % stride) == phase)) { const int task = gw + ci * NGW; ++ci;
;                 cmp_task(Z, KCC, VCT, OCMP, SELM, task >> 9, (task >> 8) & 1, (task + 64 * (task >> 11)) & 255, lane); }
.LBB0_481:
	s_mov_b64 s[48:49], exec
	s_mov_b64 exec, 1
	v_mov_b32_e32 v1, 0x20104
	v_mov_b32_e32 v2, 1
	ds_add_rtn_u32 v2, v1, v2
	s_waitcnt lgkmcnt(0)
	v_readfirstlane_b32 s8, v2
	s_mov_b64 exec, s[48:49]
	s_cmpk_lt_u32 s8, 32
	s_cbranch_scc1 .Lcmp_have
	s_mov_b32 s63, s58
	s_branch .LBB0_476
.Lcmp_have:
	s_and_b32 s9, s8, 7
	s_lshr_b32 s8, s8, 3
	s_lshr_b32 s10, s92, 6
	s_add_i32 s8, s8, s10
	s_sub_i32 s8, 3, s8
	s_and_b32 s8, s8, 3
	s_lshl_b32 s8, s8, 11
	s_add_i32 s9, s9, s8
	s_and_b32 s8, s92, -8
	s_add_i32 s9, s9, s8
	s_lshr_b32 s10, s9, 5
	s_and_b32 s10, s10, 0xc0
	s_add_i32 s10, s10, s9
	s_ashr_i32 s8, s9, 9
	s_and_b32 s54, s10, 0xff
	s_bfe_u32 s14, s9, 0x10008
	s_lshl_b32 s50, s54, 3
	s_ashr_i32 s9, s8, 31
	v_or_b32_e32 v131, s50, v113
	s_lshl_b64 s[10:11], s[8:9], 11
	v_or_b32_e32 v122, s10, v131
	v_mov_b64_e32 v[2:3], s[22:23]
	s_movk_i32 s9, 0x2200
	v_mad_u64_u32 v[2:3], s[48:49], v122, s9, v[2:3]
	v_lshl_or_b32 v1, s14, 8, v115
	v_mad_i32_i24 v3, s11, v244, v3
	v_lshlrev_b32_e32 v42, 1, v1
	v_lshl_add_u64 v[2:3], v[2:3], 0, v[42:43]
	v_mov_b32_e32 v41, v43
	v_lshl_add_u64 v[2:3], v[2:3], 0, v[40:41]
	global_load_dwordx4 v[30:33], v[2:3], off
	global_load_dwordx4 v[26:29], v[2:3], off offset:32
	global_load_dwordx4 v[22:25], v[2:3], off offset:64
	global_load_dwordx4 v[18:21], v[2:3], off offset:96
	s_lshl_b32 s8, s8, 1
	s_or_b32 s8, s8, s14
	s_ashr_i32 s9, s8, 31
	s_lshl_b64 s[8:9], s[8:9], 14
	s_or_b32 s10, s50, 7
	s_cmp_lt_u32 s10, 31
	s_cselect_b64 s[48:49], -1, 0
	s_cmp_gt_u32 s10, 30
	v_mov_b32_e32 v123, s11
	s_cselect_b64 s[10:11], -1, 0
	v_lshl_add_u64 v[124:125], v[44:45], 0, s[8:9]
	v_readfirstlane_b32 s99, v0
	s_lshr_b32 s99, s99, 6
	s_lshl_b32 s99, s99, 14
	v_readfirstlane_b32 s78, v78
	v_readfirstlane_b32 s79, v79
	s_add_u32 s78, s78, s8
	s_addc_u32 s79, s79, s9
	v_mbcnt_lo_u32_b32 v34, -1, 0
	v_mbcnt_hi_u32_b32 v34, -1, v34
	v_lshrrev_b32_e32 v35, 5, v34
	v_and_b32_e32 v34, 31, v34
	v_lshlrev_b32_e32 v34, 8, v34
	v_lshl_or_b32 v34, v35, 4, v34
	s_add_i32 m0, s99, 0x0
	s_add_u32 s80, s78, 0x0
	s_addc_u32 s81, s79, 0
	global_load_lds_dwordx4 v34, s[80:81]
	s_add_i32 m0, s99, 0x400
	s_add_u32 s80, s78, 0x20
	s_addc_u32 s81, s79, 0
	global_load_lds_dwordx4 v34, s[80:81]
	s_add_i32 m0, s99, 0x800
	s_add_u32 s80, s78, 0x40
	s_addc_u32 s81, s79, 0
	global_load_lds_dwordx4 v34, s[80:81]
	s_add_i32 m0, s99, 0xc00
	s_add_u32 s80, s78, 0x60
	s_addc_u32 s81, s79, 0
	global_load_lds_dwordx4 v34, s[80:81]
	s_add_i32 m0, s99, 0x1000
	s_add_u32 s80, s78, 0x80
	s_addc_u32 s81, s79, 0
	global_load_lds_dwordx4 v34, s[80:81]
	s_add_i32 m0, s99, 0x1400
	s_add_u32 s80, s78, 0xa0
	s_addc_u32 s81, s79, 0
	global_load_lds_dwordx4 v34, s[80:81]
	s_add_i32 m0, s99, 0x1800
	s_add_u32 s80, s78, 0xc0
	s_addc_u32 s81, s79, 0
	global_load_lds_dwordx4 v34, s[80:81]
	s_add_i32 m0, s99, 0x1c00
	s_add_u32 s80, s78, 0xe0
	s_addc_u32 s81, s79, 0
	global_load_lds_dwordx4 v34, s[80:81]
	s_add_i32 m0, s99, 0x2000
	s_add_u32 s80, s78, 0x2000
	s_addc_u32 s81, s79, 0
	global_load_lds_dwordx4 v34, s[80:81]
	s_add_i32 m0, s99, 0x2400
	s_add_u32 s80, s78, 0x2020
	s_addc_u32 s81, s79, 0
	global_load_lds_dwordx4 v34, s[80:81]
	s_add_i32 m0, s99, 0x2800
	s_add_u32 s80, s78, 0x2040
	s_addc_u32 s81, s79, 0
	global_load_lds_dwordx4 v34, s[80:81]
	s_add_i32 m0, s99, 0x2c00
	s_add_u32 s80, s78, 0x2060
	s_addc_u32 s81, s79, 0
	global_load_lds_dwordx4 v34, s[80:81]
	s_add_i32 m0, s99, 0x3000
	s_add_u32 s80, s78, 0x2080
	s_addc_u32 s81, s79, 0
	global_load_lds_dwordx4 v34, s[80:81]
	s_add_i32 m0, s99, 0x3400
	s_add_u32 s80, s78, 0x20a0
	s_addc_u32 s81, s79, 0
	global_load_lds_dwordx4 v34, s[80:81]
	s_add_i32 m0, s99, 0x3800
	s_add_u32 s80, s78, 0x20c0
	s_addc_u32 s81, s79, 0
	global_load_lds_dwordx4 v34, s[80:81]
	s_add_i32 m0, s99, 0x3c00
	s_add_u32 s80, s78, 0x20e0
	s_addc_u32 s81, s79, 0
	global_load_lds_dwordx4 v34, s[80:81]
	v_mov_b32_e32 v121, 0xff800000
	s_and_b64 vcc, exec, s[48:49]
	v_lshlrev_b32_e32 v126, 1, v38
	v_mov_b32_e32 v128, 0xff800000
	v_mov_b32_e32 v129, 0xff800000
	v_mov_b32_e32 v130, 0xff800000
	v_mov_b32_e32 v134, 0xff800000
	v_mov_b32_e32 v135, 0xff800000
	v_mov_b32_e32 v139, 0xff800000
	v_mov_b32_e32 v140, 0xff800000
	v_mov_b32_e32 v141, 0xff800000
	v_mov_b32_e32 v142, 0xff800000
	v_mov_b32_e32 v143, 0xff800000
	v_mov_b32_e32 v144, 0xff800000
	v_mov_b32_e32 v145, 0xff800000
	v_mov_b32_e32 v146, 0xff800000
	v_mov_b32_e32 v147, 0xff800000
	v_mov_b32_e32 v148, 0xff800000
	v_mov_b32_e32 v149, 0xff800000
	s_cbranch_vccnz .LBB0_483
	v_mov_b32_e32 v127, v43
	v_lshl_add_u64 v[94:95], v[124:125], 0, v[126:127]
	global_load_dwordx4 v[2:5], v[94:95], off
	global_load_dwordx4 v[140:143], v[94:95], off offset:32
	global_load_dwordx4 v[150:153], v[94:95], off offset:64
	global_load_dwordx4 v[154:157], v[94:95], off offset:96
	v_cmp_le_u32_e32 vcc, v46, v131
	s_waitcnt vmcnt(3)
	v_mfma_f32_32x32x16_bf16 v[2:17], v[2:5], v[30:33], 0
	s_waitcnt vmcnt(2)
	v_mfma_f32_32x32x16_bf16 v[2:17], v[140:143], v[26:29], v[2:17]
	s_waitcnt vmcnt(1)
	v_mfma_f32_32x32x16_bf16 v[2:17], v[150:153], v[22:25], v[2:17]
	s_waitcnt vmcnt(0)
	v_mfma_f32_32x32x16_bf16 v[2:17], v[154:157], v[18:21], v[2:17]
	s_nop 11
	v_pk_mul_f32 v[2:3], v[2:3], s[46:47] op_sel_hi:[1,0]
	s_nop 0
	v_cndmask_b32_e32 v128, v245, v2, vcc
	v_cmp_le_u32_e32 vcc, v37, v131
	v_mul_f32_e32 v1, 0x3e38aa3b, v4
	s_nop 0
	v_cndmask_b32_e32 v129, v245, v3, vcc
	v_cmp_le_u32_e32 vcc, v117, v131
	v_pk_mul_f32 v[2:3], v[6:7], s[46:47] op_sel_hi:[1,0]
	s_nop 0
	v_cndmask_b32_e32 v130, v245, v1, vcc
	v_mul_f32_e32 v1, 0x3e38aa3b, v5
	v_cmp_le_u32_e32 vcc, v119, v131
	s_nop 1
	v_cndmask_b32_e32 v134, v245, v1, vcc
	v_cmp_le_u32_e32 vcc, v48, v131
	v_mul_f32_e32 v1, 0x3e38aa3b, v8
	s_nop 0
	v_cndmask_b32_e32 v135, v245, v2, vcc
	v_cmp_le_u32_e32 vcc, v39, v131
	s_nop 1
	v_cndmask_b32_e32 v139, v245, v3, vcc
	v_cmp_le_u32_e32 vcc, v202, v131
	v_pk_mul_f32 v[2:3], v[10:11], s[46:47] op_sel_hi:[1,0]
	s_nop 0
	v_cndmask_b32_e32 v140, v245, v1, vcc
	v_mul_f32_e32 v1, 0x3e38aa3b, v9
	v_cmp_le_u32_e32 vcc, v203, v131
	s_nop 1
	v_cndmask_b32_e32 v141, v245, v1, vcc
	v_cmp_le_u32_e32 vcc, v50, v131
	v_mul_f32_e32 v1, 0x3e38aa3b, v12
	s_nop 0
	v_cndmask_b32_e32 v142, v245, v2, vcc
	v_cmp_le_u32_e32 vcc, v47, v131
	s_nop 1
	v_cndmask_b32_e32 v143, v245, v3, vcc
	v_cmp_le_u32_e32 vcc, v204, v131
	v_pk_mul_f32 v[2:3], v[14:15], s[46:47] op_sel_hi:[1,0]
	s_nop 0
	v_cndmask_b32_e32 v144, v245, v1, vcc
	v_mul_f32_e32 v1, 0x3e38aa3b, v13
	v_cmp_le_u32_e32 vcc, v205, v131
	s_nop 1
	v_cndmask_b32_e32 v145, v245, v1, vcc
	v_cmp_le_u32_e32 vcc, v52, v131
	v_mul_f32_e32 v1, 0x3e38aa3b, v16
	s_nop 0
	v_cndmask_b32_e32 v146, v245, v2, vcc
	v_cmp_le_u32_e32 vcc, v49, v131
	s_nop 1
	v_cndmask_b32_e32 v147, v245, v3, vcc
	v_cmp_le_u32_e32 vcc, v206, v131
	s_nop 1
	v_cndmask_b32_e32 v148, v245, v1, vcc
	v_mul_f32_e32 v1, 0x3e38aa3b, v17
	v_cmp_le_u32_e32 vcc, v207, v131
	s_nop 1
	v_cndmask_b32_e32 v149, v245, v1, vcc
